# hyena out-proj epilogue regenerated: gate/bias vectors loaded once, residual rows loaded per fragment group, 16-byte stores via v_permlane16_swap
# speedup vs baseline: 1.0606x; 1.0062x over previous
; template <bool SWAP, class Epi, bool THIN = false> ...
;     ...
;     for (int st = 0; st < ns; ++st) {
;       asm volatile("s_waitcnt vmcnt(0)" ::: "memory");
;       __builtin_amdgcn_s_barrier();
;       asm volatile("" ::: "memory");
;       if (st + 1 < ns) {
;         char* nb = smem + ((st + 1) & 1) * 65536;
;         const int ko = (st + 1) * 64;
; #pragma unroll
;         for (int i = 0; i < 4; ++i) { GLDS16(A + (size_t)(ap[i] + ko), nb + tid * 16 + i * 8192); GLDS16(Bt + (size_t)(bp[i] + ko), nb + 32768 + tid * 16 + i * 8192); }
;       }
;       const char* sa = smem + (st & 1) * 65536 + (wr * 64 + fr) * 128;
;       const char* sb = smem + (st & 1) * 65536 + 32768 + (wc * 128 + fr) * 128;
;       if constexpr (THIN) {
;         if (wc == 0) {
; #pragma unroll
;           for (int ks = 0; ks < 2; ++ks) {
;             bf16x8 af[4], bf[2];
; #pragma unroll
;             for (int m = 0; m < 4; ++m) af[m] = *(const bf16x8*)(sa + m * 2048 + (((ks * 4 + fq) ^ swz) << 4));
; #pragma unroll
;             for (int n = 0; n < 2; ++n) bf[n] = *(const bf16x8*)(sb + n * 2048 + (((ks * 4 + fq) ^ swz) << 4));
; #pragma unroll
;             for (int m = 0; m < 4; ++m)
; #pragma unroll
;               for (int n = 0; n < 2; ++n)
;                 acc[m][n] = SWAP ? __builtin_amdgcn_mfma_f32_16x16x32_bf16(bf[n], af[m], acc[m][n], 0, 0, 0)
;                                  : __builtin_amdgcn_mfma_f32_16x16x32_bf16(af[m], bf[n], acc[m][n], 0, 0, 0);
;           }
;         }
;       } else {
;       bf16x8 afA[4], afB[4], bfb[2][2];
; #pragma unroll
;       for (int m = 0; m < 4; ++m) afA[m] = *(const bf16x8*)(sa + m * 2048 + ((fq ^ swz) << 4));
; #pragma unroll
;       for (int n = 0; n < 2; ++n) bfb[0][n] = *(const bf16x8*)(sb + n * 2048 + ((fq ^ swz) << 4));
; #pragma unroll
;       for (int gq = 0; gq < 8; ++gq) {
;         const int ks = gq >> 2, nh = gq & 3;
;         if (gq < 7) {
;           const int ks2 = (gq + 1) >> 2, nh2 = (gq + 1) & 3;
; #pragma unroll
;           for (int n = 0; n < 2; ++n) bfb[(gq + 1) & 1][n] = *(const bf16x8*)(sb + (nh2 * 2 + n) * 2048 + (((ks2 * 4 + fq) ^ swz) << 4));
;         }
;         if (gq == 3) {
; #pragma unroll
;           for (int m = 0; m < 4; ++m) afB[m] = *(const bf16x8*)(sa + m * 2048 + (((4 + fq) ^ swz) << 4));
;         }
;         __builtin_amdgcn_sched_barrier(0);
; #pragma unroll
.LBB0_3112:
	s_add_i32 s9, s7, 0x10000
	s_and_b32 s8, s9, 0x10000
	v_add_u32_e32 v142, s8, v156
	s_nop 0
	v_readfirstlane_b32 s10, v142
	s_waitcnt vmcnt(0)
	s_barrier
	s_and_b32 s7, s7, 0x10000
	v_add_u32_e32 v138, s7, v157
	v_add_u32_e32 v152, v138, v159
	ds_read_b128 v[140:143], v152
	ds_read_b128 v[144:147], v152 offset:2048
	ds_read_b128 v[148:151], v152 offset:4096
	ds_read_b128 v[180:183], v152 offset:6144
	v_or_b32_e32 v152, s7, v158
	v_add_u32_e32 v153, v152, v159
	ds_read_b128 v[184:187], v153 offset:32768
	ds_read_b128 v[188:191], v153 offset:34816
	ds_read_b128 v[192:195], v153 offset:36864
	ds_read_b128 v[196:199], v153 offset:38912
	v_add_u32_e32 v138, v138, v160
	s_waitcnt lgkmcnt(3)
	v_mfma_f32_16x16x32_bf16 v[126:129], v[184:187], v[140:143], v[126:129]
	s_mov_b32 m0, s10
	v_mfma_f32_16x16x32_bf16 v[110:113], v[184:187], v[144:147], v[110:113]
	global_load_lds_dwordx4 v137, s[22:23]
	v_add_u32_e32 v137, 0x80, v137
	v_mfma_f32_16x16x32_bf16 v[82:85], v[184:187], v[148:151], v[82:85]
	v_mfma_f32_16x16x32_bf16 v[50:53], v[184:187], v[180:183], v[50:53]
	ds_read_b128 v[184:187], v153 offset:40960
	ds_read_b128 v[200:203], v153 offset:43008
	s_waitcnt lgkmcnt(4)
	v_mfma_f32_16x16x32_bf16 v[122:125], v[188:191], v[140:143], v[122:125]
	s_add_u32 m0, s10, 0x8000
	v_mfma_f32_16x16x32_bf16 v[106:109], v[188:191], v[144:147], v[106:109]
	global_load_lds_dwordx4 v136, s[28:29]
	v_add_u32_e32 v136, 0x80, v136
	v_mfma_f32_16x16x32_bf16 v[78:81], v[188:191], v[148:151], v[78:81]
	v_mfma_f32_16x16x32_bf16 v[38:41], v[188:191], v[180:183], v[38:41]
	s_waitcnt lgkmcnt(3)
	v_mfma_f32_16x16x32_bf16 v[118:121], v[192:195], v[140:143], v[118:121]
	s_add_u32 m0, s10, 0x2000
	v_mfma_f32_16x16x32_bf16 v[94:97], v[192:195], v[144:147], v[94:97]
	global_load_lds_dwordx4 v135, s[22:23]
	v_add_u32_e32 v135, 0x80, v135
	v_mfma_f32_16x16x32_bf16 v[58:61], v[192:195], v[148:151], v[58:61]
	v_mfma_f32_16x16x32_bf16 v[26:29], v[192:195], v[180:183], v[26:29]
	ds_read_b128 v[188:191], v153 offset:45056
	ds_read_b128 v[192:195], v153 offset:47104
	s_waitcnt lgkmcnt(4)
	v_mfma_f32_16x16x32_bf16 v[114:117], v[196:199], v[140:143], v[114:117]
	s_add_u32 m0, s10, 0xa000
	v_mfma_f32_16x16x32_bf16 v[86:89], v[196:199], v[144:147], v[86:89]
	global_load_lds_dwordx4 v134, s[28:29]
	v_add_u32_e32 v134, 0x80, v134
	v_mfma_f32_16x16x32_bf16 v[54:57], v[196:199], v[148:151], v[54:57]
	v_mfma_f32_16x16x32_bf16 v[22:25], v[196:199], v[180:183], v[22:25]
	v_add_u32_e32 v152, v152, v160
	s_waitcnt lgkmcnt(3)
	v_mfma_f32_16x16x32_bf16 v[102:105], v[184:187], v[140:143], v[102:105]
	ds_read_b128 v[196:199], v152 offset:32768
	ds_read_b128 v[204:207], v152 offset:34816
	s_add_u32 m0, s10, 0x4000
	v_mfma_f32_16x16x32_bf16 v[74:77], v[184:187], v[144:147], v[74:77]
	global_load_lds_dwordx4 v133, s[22:23]
	v_add_u32_e32 v133, 0x80, v133
	v_mfma_f32_16x16x32_bf16 v[46:49], v[184:187], v[148:151], v[46:49]
	v_mfma_f32_16x16x32_bf16 v[10:13], v[184:187], v[180:183], v[10:13]
	ds_read_b128 v[184:187], v138
	ds_read_b128 v[208:211], v138 offset:2048
	ds_read_b128 v[212:215], v138 offset:4096
	ds_read_b128 v[216:219], v138 offset:6144
	s_waitcnt lgkmcnt(8)
	v_mfma_f32_16x16x32_bf16 v[98:101], v[200:203], v[140:143], v[98:101]
	s_add_u32 m0, s10, 0xc000
	v_mfma_f32_16x16x32_bf16 v[66:69], v[200:203], v[144:147], v[66:69]
	global_load_lds_dwordx4 v132, s[28:29]
	v_add_u32_e32 v132, 0x80, v132
	v_mfma_f32_16x16x32_bf16 v[34:37], v[200:203], v[148:151], v[34:37]
	v_mfma_f32_16x16x32_bf16 v[6:9], v[200:203], v[180:183], v[6:9]
	s_waitcnt lgkmcnt(7)
	v_mfma_f32_16x16x32_bf16 v[70:73], v[188:191], v[140:143], v[70:73]
	s_add_u32 m0, s10, 0x6000
	s_waitcnt lgkmcnt(6)
	v_mfma_f32_16x16x32_bf16 v[62:65], v[192:195], v[140:143], v[62:65]
	global_load_lds_dwordx4 v131, s[22:23]
	v_add_u32_e32 v131, 0x80, v131
	v_mfma_f32_16x16x32_bf16 v[42:45], v[188:191], v[144:147], v[42:45]
	v_mfma_f32_16x16x32_bf16 v[30:33], v[192:195], v[144:147], v[30:33]
	ds_read_b128 v[140:143], v152 offset:36864
	ds_read_b128 v[144:147], v152 offset:38912
	v_mfma_f32_16x16x32_bf16 v[18:21], v[188:191], v[148:151], v[18:21]
	s_add_u32 m0, s10, 0xe000
	v_mfma_f32_16x16x32_bf16 v[14:17], v[192:195], v[148:151], v[14:17]
	global_load_lds_dwordx4 v130, s[28:29]
	v_add_u32_e32 v130, 0x80, v130
	v_mfma_f32_16x16x32_bf16 v[2:5], v[188:191], v[180:183], v[2:5]
	v_mfma_f32_16x16x32_bf16 v[90:93], v[192:195], v[180:183], v[90:93]
	ds_read_b128 v[148:151], v152 offset:40960
	ds_read_b128 v[180:183], v152 offset:43008
	s_waitcnt lgkmcnt(7)
	v_mfma_f32_16x16x32_bf16 v[126:129], v[196:199], v[184:187], v[126:129]
	v_mfma_f32_16x16x32_bf16 v[122:125], v[204:207], v[184:187], v[122:125]
	s_waitcnt lgkmcnt(6)
	v_mfma_f32_16x16x32_bf16 v[110:113], v[196:199], v[208:211], v[110:113]
	v_mfma_f32_16x16x32_bf16 v[106:109], v[204:207], v[208:211], v[106:109]
	s_waitcnt lgkmcnt(5)
	v_mfma_f32_16x16x32_bf16 v[82:85], v[196:199], v[212:215], v[82:85]
	v_mfma_f32_16x16x32_bf16 v[78:81], v[204:207], v[212:215], v[78:81]
	s_waitcnt lgkmcnt(4)
	v_mfma_f32_16x16x32_bf16 v[50:53], v[196:199], v[216:219], v[50:53]
	v_mfma_f32_16x16x32_bf16 v[38:41], v[204:207], v[216:219], v[38:41]
	s_waitcnt lgkmcnt(3)
	v_mfma_f32_16x16x32_bf16 v[118:121], v[140:143], v[184:187], v[118:121]
	v_mfma_f32_16x16x32_bf16 v[94:97], v[140:143], v[208:211], v[94:97]
	v_mfma_f32_16x16x32_bf16 v[58:61], v[140:143], v[212:215], v[58:61]
	v_mfma_f32_16x16x32_bf16 v[26:29], v[140:143], v[216:219], v[26:29]
	ds_read_b128 v[140:143], v152 offset:45056
	ds_read_b128 v[188:191], v152 offset:47104
	s_waitcnt lgkmcnt(4)
; template <bool SWAP, class Epi, bool THIN = false> ...
;     ...
;     for (int st = 0; st < ns; ++st) {
;       asm volatile("s_waitcnt vmcnt(0)" ::: "memory");
;       __builtin_amdgcn_s_barrier();
;       asm volatile("" ::: "memory");
;       if (st + 1 < ns) {
;         char* nb = smem + ((st + 1) & 1) * 65536;
;         const int ko = (st + 1) * 64;
; #pragma unroll
;         for (int i = 0; i < 4; ++i) { GLDS16(A + (size_t)(ap[i] + ko), nb + tid * 16 + i * 8192); GLDS16(Bt + (size_t)(bp[i] + ko), nb + 32768 + tid * 16 + i * 8192); }
;       }
;       const char* sa = smem + (st & 1) * 65536 + (wr * 64 + fr) * 128;
;       const char* sb = smem + (st & 1) * 65536 + 32768 + (wc * 128 + fr) * 128;
;       if constexpr (THIN) {
;         if (wc == 0) {
; #pragma unroll
;           for (int ks = 0; ks < 2; ++ks) {
;             bf16x8 af[4], bf[2];
; #pragma unroll
;             for (int m = 0; m < 4; ++m) af[m] = *(const bf16x8*)(sa + m * 2048 + (((ks * 4 + fq) ^ swz) << 4));
; #pragma unroll
;             for (int n = 0; n < 2; ++n) bf[n] = *(const bf16x8*)(sb + n * 2048 + (((ks * 4 + fq) ^ swz) << 4));
; #pragma unroll
;             for (int m = 0; m < 4; ++m)
; #pragma unroll
;               for (int n = 0; n < 2; ++n)
;                 acc[m][n] = SWAP ? __builtin_amdgcn_mfma_f32_16x16x32_bf16(bf[n], af[m], acc[m][n], 0, 0, 0)
;                                  : __builtin_amdgcn_mfma_f32_16x16x32_bf16(af[m], bf[n], acc[m][n], 0, 0, 0);
;           }
;         }
;       } else {
;       bf16x8 afA[4], afB[4], bfb[2][2];
; #pragma unroll
;       for (int m = 0; m < 4; ++m) afA[m] = *(const bf16x8*)(sa + m * 2048 + ((fq ^ swz) << 4));
; #pragma unroll
;       for (int n = 0; n < 2; ++n) bfb[0][n] = *(const bf16x8*)(sb + n * 2048 + ((fq ^ swz) << 4));
; #pragma unroll
;       for (int gq = 0; gq < 8; ++gq) {
;         const int ks = gq >> 2, nh = gq & 3;
;         if (gq < 7) {
;           const int ks2 = (gq + 1) >> 2, nh2 = (gq + 1) & 3;
; #pragma unroll
;           for (int n = 0; n < 2; ++n) bfb[(gq + 1) & 1][n] = *(const bf16x8*)(sb + (nh2 * 2 + n) * 2048 + (((ks2 * 4 + fq) ^ swz) << 4));
;         }
;         if (gq == 3) {
; #pragma unroll
;           for (int m = 0; m < 4; ++m) afB[m] = *(const bf16x8*)(sa + m * 2048 + (((4 + fq) ^ swz) << 4));
;         }
;         __builtin_amdgcn_sched_barrier(0);
; #pragma unroll
	v_mfma_f32_16x16x32_bf16 v[114:117], v[144:147], v[184:187], v[114:117]
	v_mfma_f32_16x16x32_bf16 v[86:89], v[144:147], v[208:211], v[86:89]
	v_mfma_f32_16x16x32_bf16 v[54:57], v[144:147], v[212:215], v[54:57]
	v_mfma_f32_16x16x32_bf16 v[22:25], v[144:147], v[216:219], v[22:25]
	s_waitcnt lgkmcnt(3)
	v_mfma_f32_16x16x32_bf16 v[102:105], v[148:151], v[184:187], v[102:105]
	s_waitcnt lgkmcnt(2)
	v_mfma_f32_16x16x32_bf16 v[98:101], v[180:183], v[184:187], v[98:101]
	v_mfma_f32_16x16x32_bf16 v[74:77], v[148:151], v[208:211], v[74:77]
	v_mfma_f32_16x16x32_bf16 v[66:69], v[180:183], v[208:211], v[66:69]
	v_mfma_f32_16x16x32_bf16 v[46:49], v[148:151], v[212:215], v[46:49]
	v_mfma_f32_16x16x32_bf16 v[34:37], v[180:183], v[212:215], v[34:37]
	v_mfma_f32_16x16x32_bf16 v[10:13], v[148:151], v[216:219], v[10:13]
	v_mfma_f32_16x16x32_bf16 v[6:9], v[180:183], v[216:219], v[6:9]
	s_waitcnt lgkmcnt(1)
	v_mfma_f32_16x16x32_bf16 v[70:73], v[140:143], v[184:187], v[70:73]
	s_add_i32 s6, s6, 64
	s_cmpk_eq_i32 s6, 0x3c0
	s_mov_b32 s7, s9
	s_waitcnt lgkmcnt(0)
	v_mfma_f32_16x16x32_bf16 v[62:65], v[188:191], v[184:187], v[62:65]
	v_mfma_f32_16x16x32_bf16 v[42:45], v[140:143], v[208:211], v[42:45]
	v_mfma_f32_16x16x32_bf16 v[30:33], v[188:191], v[208:211], v[30:33]
	v_mfma_f32_16x16x32_bf16 v[18:21], v[140:143], v[212:215], v[18:21]
	v_mfma_f32_16x16x32_bf16 v[14:17], v[188:191], v[212:215], v[14:17]
	v_mfma_f32_16x16x32_bf16 v[2:5], v[140:143], v[216:219], v[2:5]
	v_mfma_f32_16x16x32_bf16 v[90:93], v[188:191], v[216:219], v[90:93]
	s_cbranch_scc0 .LBB0_3112
	v_add_u32_e32 v138, s8, v157
	v_add_u32_e32 v152, s8, v158
	s_waitcnt vmcnt(0)
	s_barrier
	v_add_u32_e32 v144, v138, v159
	v_add_u32_e32 v153, v152, v159
	ds_read_b128 v[130:133], v144
	ds_read_b128 v[134:137], v144 offset:2048
	ds_read_b128 v[140:143], v144 offset:4096
	ds_read_b128 v[144:147], v144 offset:6144
	ds_read_b128 v[148:151], v153 offset:32768
	ds_read_b128 v[180:183], v153 offset:34816
	ds_read_b128 v[184:187], v153 offset:36864
	ds_read_b128 v[188:191], v153 offset:38912
	v_add_u32_e32 v138, v138, v160
	s_waitcnt lgkmcnt(0)
	v_mfma_f32_16x16x32_bf16 v[126:129], v[148:151], v[130:133], v[126:129]
	v_mfma_f32_16x16x32_bf16 v[110:113], v[148:151], v[134:137], v[110:113]
	v_mfma_f32_16x16x32_bf16 v[82:85], v[148:151], v[140:143], v[82:85]
	v_mfma_f32_16x16x32_bf16 v[50:53], v[148:151], v[144:147], v[50:53]
	ds_read_b128 v[148:151], v153 offset:40960
	ds_read_b128 v[192:195], v153 offset:43008
	v_mfma_f32_16x16x32_bf16 v[122:125], v[180:183], v[130:133], v[122:125]
	v_mfma_f32_16x16x32_bf16 v[106:109], v[180:183], v[134:137], v[106:109]
	v_mfma_f32_16x16x32_bf16 v[78:81], v[180:183], v[140:143], v[78:81]
	v_mfma_f32_16x16x32_bf16 v[38:41], v[180:183], v[144:147], v[38:41]
	v_mfma_f32_16x16x32_bf16 v[118:121], v[184:187], v[130:133], v[118:121]
	v_mfma_f32_16x16x32_bf16 v[180:183], v[184:187], v[134:137], v[94:97]
	v_mfma_f32_16x16x32_bf16 v[200:203], v[184:187], v[140:143], v[58:61]
	v_mfma_f32_16x16x32_bf16 v[204:207], v[188:191], v[140:143], v[54:57]
	v_mfma_f32_16x16x32_bf16 v[184:187], v[184:187], v[144:147], v[26:29]
	s_nop 2
	ds_read_b128 v[26:29], v153 offset:45056
	ds_read_b128 v[54:57], v153 offset:47104
	v_mfma_f32_16x16x32_bf16 v[114:117], v[188:191], v[130:133], v[114:117]
	v_mfma_f32_16x16x32_bf16 v[196:199], v[188:191], v[134:137], v[86:89]
	v_mfma_f32_16x16x32_bf16 v[188:191], v[188:191], v[144:147], v[22:25]
	v_add_u32_e32 v152, v152, v160
	s_waitcnt lgkmcnt(0)
	v_mfma_f32_16x16x32_bf16 v[102:105], v[148:151], v[130:133], v[102:105]
	ds_read_b128 v[22:25], v152 offset:32768
	ds_read_b128 v[86:89], v152 offset:34816
	v_mfma_f32_16x16x32_bf16 v[74:77], v[148:151], v[134:137], v[74:77]
	v_mfma_f32_16x16x32_bf16 v[46:49], v[148:151], v[140:143], v[46:49]
	v_mfma_f32_16x16x32_bf16 v[10:13], v[148:151], v[144:147], v[10:13]
	ds_read_b128 v[148:151], v138
	ds_read_b128 v[208:211], v138 offset:2048
	ds_read_b128 v[212:215], v138 offset:4096
	ds_read_b128 v[216:219], v138 offset:6144
	v_mfma_f32_16x16x32_bf16 v[98:101], v[192:195], v[130:133], v[98:101]
	v_mfma_f32_16x16x32_bf16 v[66:69], v[192:195], v[134:137], v[66:69]
	v_mfma_f32_16x16x32_bf16 v[34:37], v[192:195], v[140:143], v[34:37]
	v_mfma_f32_16x16x32_bf16 v[6:9], v[192:195], v[144:147], v[6:9]
	v_mfma_f32_16x16x32_bf16 v[220:223], v[26:29], v[140:143], v[18:21]
	v_mfma_f32_16x16x32_bf16 v[140:143], v[54:57], v[140:143], v[14:17]
	s_nop 2
	ds_read_b128 v[14:17], v152 offset:36864
	ds_read_b128 v[18:21], v152 offset:38912
	v_mfma_f32_16x16x32_bf16 v[70:73], v[26:29], v[130:133], v[70:73]
	v_mfma_f32_16x16x32_bf16 v[2:5], v[26:29], v[144:147], v[2:5]
	v_mfma_f32_16x16x32_bf16 v[130:133], v[54:57], v[130:133], v[62:65]
	v_mfma_f32_16x16x32_bf16 v[192:195], v[26:29], v[134:137], v[42:45]
	v_mfma_f32_16x16x32_bf16 v[134:137], v[54:57], v[134:137], v[30:33]
	v_mfma_f32_16x16x32_bf16 v[224:227], v[54:57], v[144:147], v[90:93]
	ds_read_b128 v[144:147], v152 offset:40960
	ds_read_b128 v[228:231], v152 offset:43008
	s_waitcnt lgkmcnt(0)
	v_mfma_f32_16x16x32_bf16 v[126:129], v[22:25], v[148:151], v[126:129]
	v_mfma_f32_16x16x32_bf16 v[122:125], v[86:89], v[148:151], v[122:125]
	v_mfma_f32_16x16x32_bf16 v[94:97], v[22:25], v[208:211], v[110:113]
	v_mfma_f32_16x16x32_bf16 v[90:93], v[86:89], v[208:211], v[106:109]
	v_mfma_f32_16x16x32_bf16 v[62:65], v[22:25], v[212:215], v[82:85]
	v_mfma_f32_16x16x32_bf16 v[58:61], v[86:89], v[212:215], v[78:81]
	v_mfma_f32_16x16x32_bf16 v[30:33], v[22:25], v[216:219], v[50:53]
	v_mfma_f32_16x16x32_bf16 v[26:29], v[86:89], v[216:219], v[38:41]
	v_mfma_f32_16x16x32_bf16 v[86:89], v[14:17], v[208:211], v[180:183]
	v_mfma_f32_16x16x32_bf16 v[22:25], v[14:17], v[216:219], v[184:187]
	s_nop 1
	ds_read_b128 v[180:183], v152 offset:45056
	ds_read_b128 v[184:187], v152 offset:47104
	v_mfma_f32_16x16x32_bf16 v[118:121], v[14:17], v[148:151], v[118:121]
	v_mfma_f32_16x16x32_bf16 v[114:117], v[18:21], v[148:151], v[114:117]
	v_mfma_f32_16x16x32_bf16 v[82:85], v[18:21], v[208:211], v[196:199]
	v_mfma_f32_16x16x32_bf16 v[54:57], v[14:17], v[212:215], v[200:203]
	v_mfma_f32_16x16x32_bf16 v[50:53], v[18:21], v[212:215], v[204:207]
	v_mfma_f32_16x16x32_bf16 v[18:21], v[18:21], v[216:219], v[188:191]
	v_mfma_f32_16x16x32_bf16 v[110:113], v[144:147], v[148:151], v[102:105]
	v_mfma_f32_16x16x32_bf16 v[106:109], v[228:231], v[148:151], v[98:101]
	v_mfma_f32_16x16x32_bf16 v[78:81], v[144:147], v[208:211], v[74:77]
	v_mfma_f32_16x16x32_bf16 v[74:77], v[228:231], v[208:211], v[66:69]
	v_mfma_f32_16x16x32_bf16 v[46:49], v[144:147], v[212:215], v[46:49]
	v_mfma_f32_16x16x32_bf16 v[42:45], v[228:231], v[212:215], v[34:37]
	v_mfma_f32_16x16x32_bf16 v[14:17], v[144:147], v[216:219], v[10:13]
	v_mfma_f32_16x16x32_bf16 v[10:13], v[228:231], v[216:219], v[6:9]
	v_mov_b32_e32 v138, v1
	s_waitcnt vmcnt(0) lgkmcnt(0)
	s_barrier
; __device__ __forceinline__ int get_tid512() { int t = threadIdx.x; asm volatile("" : "+v"(t)); return t; }
; __device__ __forceinline__ unsigned pack2(float a, float b) { unsigned r; asm("v_cvt_pk_bf16_f32 %0, %1, %2" : "=v"(r) : "v"(a), "v"(b)); return r; }
; __device__ __forceinline__ float bf2f(bf16_t h) { return __uint_as_float(((unsigned)h) << 16); }
;   __device__ __forceinline__ void c4(int g, int rig, int col, f32x4 v) const {
;     const size_t o = ((size_t)g * 2048 + rig) * 1024 + col;
;     f32x4 bs;
;     if (BASE_F32) bs = __builtin_nontemporal_load((const f32x4*)((const float*)base + o));
;     else {
;       const uint2 u = *(const uint2*)((const bf16_t*)base + o);
;       bs[0] = bf2f((bf16_t)(u.x & 0xffff)); bs[1] = bf2f((bf16_t)(u.x >> 16)); bs[2] = bf2f((bf16_t)(u.y & 0xffff)); bs[3] = bf2f((bf16_t)(u.y >> 16));
;     }
;     const f32x4 gt = *(const f32x4*)(gate + (size_t)g * 6144 + col);
;     f32x4 bi = {0.f, 0.f, 0.f, 0.f};
;     if (bias) bi = *(const f32x4*)(bias + col);
;     f32x4 r;
; #pragma unroll
;     for (int j = 0; j < 4; ++j) r[j] = bs[j] + gt[j] * (v[j] + bi[j]);
;     uint2 w; w.x = pack2(r[0], r[1]); w.y = pack2(r[2], r[3]);
;     *(uint2*)(X16 + o) = w;
;   }
; template <bool SWAP, class Epi, bool THIN = false> ...
;     ...
;     const int te = get_tid512();
;     const int fr_e = te & 15, fq_e = (te & 63) >> 4, wr_e = te >> 7, wc_e = (te >> 6) & 1;
;     const int sub = 2 * mt + (wr_e >> 1);
;     const int g = sub / tpg, ti = sub - g * tpg;
;     const int rig0 = ti * step - halo;
;     const int rw = (wr_e & 1) * 64;
;     if constexpr (Epi::KIND == 0) {
; #pragma unroll
;       for (int m = 0; m < 4; ++m) {
;         const int rig = rig0 + rw + m * 16 + fr_e;
;         if constexpr (Epi::ROWSUM) {
;           float ss = 0.f;
; #pragma unroll
;           for (int n = 0; n < 8; ++n) {
;             const int col = nt * 256 + wc_e * 128 + n * 16 + fq_e * 4;
;             if (col < N) ss += epi.c4(g, rig, col, acc[m][n]);
;           }
;           ss += __shfl_xor(ss, 16); ss += __shfl_xor(ss, 32);
;           if (fq_e == 0) epi.rowsum(g, rig, nt * 2 + wc_e, ss);
;         } else {
; #pragma unroll
;           for (int n = 0; n < 8; ++n) {
;             const int col = nt * 256 + wc_e * 128 + n * 16 + fq_e * 4;
;             if (col < N) epi.c4(g, rig, col, acc[m][n]);
;           }
;         }
	v_mfma_f32_16x16x32_bf16 v[98:101], v[184:187], v[148:151], v[130:133]
	v_ashrrev_i32_e32 v7, 8, v138
	v_add_u32_e32 v7, s5, v7
	v_ashrrev_i32_e32 v8, 31, v7
	v_lshrrev_b32_e32 v8, 28, v8
	v_add_u32_e32 v8, v7, v8
	v_ashrrev_i32_e32 v130, 4, v8
	v_lshlrev_b32_e32 v8, 11, v130
	v_lshlrev_b32_e32 v7, 7, v7
	v_sub_u32_e32 v7, v7, v8
	v_lshrrev_b32_e32 v8, 1, v138
	v_and_b32_e32 v6, 15, v138
	v_and_b32_e32 v8, 64, v8
	v_or3_b32 v144, v7, v8, v6
	v_lshlrev_b32_e32 v6, 1, v138
	v_and_b32_e32 v131, 0x80, v6
	v_mfma_f32_16x16x32_bf16 v[6:9], v[180:183], v[216:219], v[2:5]
	v_ashrrev_i32_e32 v145, 31, v144
	v_lshlrev_b64 v[132:133], 10, v[144:145]
	s_nop 0
	v_lshrrev_b32_e32 v2, 2, v138
	v_and_b32_e32 v2, 12, v2
	v_mfma_f32_16x16x32_bf16 v[102:105], v[180:183], v[148:151], v[70:73]
	v_mfma_f32_16x16x32_bf16 v[70:73], v[180:183], v[208:211], v[192:195]
	v_mfma_f32_16x16x32_bf16 v[66:69], v[184:187], v[208:211], v[134:137]
	v_mfma_f32_16x16x32_bf16 v[38:41], v[180:183], v[212:215], v[220:223]
	v_mfma_f32_16x16x32_bf16 v[34:37], v[184:187], v[212:215], v[140:143]
	s_nop 2
	v_or3_b32 v140, v2, v131, s4
	v_mfma_f32_16x16x32_bf16 v[2:5], v[184:187], v[216:219], v[224:227]
	v_ashrrev_i32_e32 v131, 31, v130
	v_lshlrev_b64 v[146:147], 21, v[130:131]
	v_mad_i64_i32 v[130:131], s[4:5], v130, s39, 0
	v_lshl_add_u64 v[132:133], v[132:133], 0, v[146:147]
	v_lshl_add_u64 v[142:143], s[30:31], 0, v[130:131]
	v_cndmask_b32_e64 v130, 0, 1, s[34:35]
	v_cmp_gt_i32_e64 s[6:7], s40, v140
	v_ashrrev_i32_e32 v141, 31, v140
	v_lshl_add_u64 v[148:149], v[132:133], 1, s[24:25]
	v_cmp_ne_u32_e64 s[4:5], 1, v130
	v_bfe_u32 v248, v1, 4, 1
	v_mul_u32_u24_e32 v248, 24, v248
	v_mov_b32_e32 v249, 0
	v_lshl_add_u64 v[130:131], v[140:141], 2, v[142:143]
	global_load_dwordx4 v[180:183], v[130:131], off
	global_load_dwordx4 v[184:187], v[130:131], off offset:64
	global_load_dwordx4 v[188:191], v[130:131], off offset:128
	global_load_dwordx4 v[192:195], v[130:131], off offset:192
	global_load_dwordx4 v[196:199], v[130:131], off offset:256
	global_load_dwordx4 v[200:203], v[130:131], off offset:320
	global_load_dwordx4 v[204:207], v[130:131], off offset:384
	global_load_dwordx4 v[208:211], v[130:131], off offset:448
	s_and_b64 vcc, exec, s[4:5]
	s_cbranch_vccnz .Lhout_nobias
	v_lshl_add_u64 v[132:133], v[140:141], 2, s[26:27]
	global_load_dwordx4 v[212:215], v[132:133], off
	global_load_dwordx4 v[216:219], v[132:133], off offset:64
	global_load_dwordx4 v[220:223], v[132:133], off offset:128
	global_load_dwordx4 v[224:227], v[132:133], off offset:192
	global_load_dwordx4 v[228:231], v[132:133], off offset:256
	global_load_dwordx4 v[232:235], v[132:133], off offset:320
	global_load_dwordx4 v[236:239], v[132:133], off offset:384
	global_load_dwordx4 v[240:243], v[132:133], off offset:448
	s_branch .Lhout_bias
.Lhout_nobias:
	v_mov_b32_e32 v212, 0
	v_mov_b32_e32 v213, 0
	v_mov_b32_e32 v214, 0
	v_mov_b32_e32 v215, 0
	v_mov_b32_e32 v216, 0
	v_mov_b32_e32 v217, 0
	v_mov_b32_e32 v218, 0
	v_mov_b32_e32 v219, 0
	v_mov_b32_e32 v220, 0
	v_mov_b32_e32 v221, 0
	v_mov_b32_e32 v222, 0
	v_mov_b32_e32 v223, 0
	v_mov_b32_e32 v224, 0
	v_mov_b32_e32 v225, 0
	v_mov_b32_e32 v226, 0
	v_mov_b32_e32 v227, 0
	v_mov_b32_e32 v228, 0
	v_mov_b32_e32 v229, 0
	v_mov_b32_e32 v230, 0
	v_mov_b32_e32 v231, 0
	v_mov_b32_e32 v232, 0
	v_mov_b32_e32 v233, 0
	v_mov_b32_e32 v234, 0
	v_mov_b32_e32 v235, 0
	v_mov_b32_e32 v236, 0
	v_mov_b32_e32 v237, 0
	v_mov_b32_e32 v238, 0
	v_mov_b32_e32 v239, 0
	v_mov_b32_e32 v240, 0
	v_mov_b32_e32 v241, 0
	v_mov_b32_e32 v242, 0
	v_mov_b32_e32 v243, 0
.Lhout_bias:
	s_waitcnt vmcnt(0)
	v_add_f32_e32 v126, v126, v212
	v_add_f32_e32 v127, v127, v213
	v_add_f32_e32 v128, v128, v214
	v_add_f32_e32 v129, v129, v215
	v_add_f32_e32 v122, v122, v216
	v_add_f32_e32 v123, v123, v217
	v_add_f32_e32 v124, v124, v218
	v_add_f32_e32 v125, v125, v219
	v_add_f32_e32 v118, v118, v220
	v_add_f32_e32 v119, v119, v221
	v_add_f32_e32 v120, v120, v222
	v_add_f32_e32 v121, v121, v223
	v_add_f32_e32 v114, v114, v224
	v_add_f32_e32 v115, v115, v225
	v_add_f32_e32 v116, v116, v226
	v_add_f32_e32 v117, v117, v227
	v_add_f32_e32 v110, v110, v228
	v_add_f32_e32 v111, v111, v229
	v_add_f32_e32 v112, v112, v230
	v_add_f32_e32 v113, v113, v231
	v_add_f32_e32 v106, v106, v232
	v_add_f32_e32 v107, v107, v233
	v_add_f32_e32 v108, v108, v234
	v_add_f32_e32 v109, v109, v235
	v_add_f32_e32 v102, v102, v236
	v_add_f32_e32 v103, v103, v237
	v_add_f32_e32 v104, v104, v238
	v_add_f32_e32 v105, v105, v239
	v_add_f32_e32 v98, v98, v240
	v_add_f32_e32 v99, v99, v241
	v_add_f32_e32 v100, v100, v242
	v_add_f32_e32 v101, v101, v243
	v_add_f32_e32 v94, v94, v212
	v_add_f32_e32 v95, v95, v213
	v_add_f32_e32 v96, v96, v214
	v_add_f32_e32 v97, v97, v215
	v_add_f32_e32 v90, v90, v216
	v_add_f32_e32 v91, v91, v217
	v_add_f32_e32 v92, v92, v218
	v_add_f32_e32 v93, v93, v219
	v_add_f32_e32 v86, v86, v220
	v_add_f32_e32 v87, v87, v221
	v_add_f32_e32 v88, v88, v222
	v_add_f32_e32 v89, v89, v223
	v_add_f32_e32 v82, v82, v224
	v_add_f32_e32 v83, v83, v225
	v_add_f32_e32 v84, v84, v226
	v_add_f32_e32 v85, v85, v227
	v_add_f32_e32 v78, v78, v228
	v_add_f32_e32 v79, v79, v229
	v_add_f32_e32 v80, v80, v230
	v_add_f32_e32 v81, v81, v231
	v_add_f32_e32 v74, v74, v232
	v_add_f32_e32 v75, v75, v233
	v_add_f32_e32 v76, v76, v234
	v_add_f32_e32 v77, v77, v235
	v_add_f32_e32 v70, v70, v236
	v_add_f32_e32 v71, v71, v237
	v_add_f32_e32 v72, v72, v238
	v_add_f32_e32 v73, v73, v239
	v_add_f32_e32 v66, v66, v240
	v_add_f32_e32 v67, v67, v241
	v_add_f32_e32 v68, v68, v242
	v_add_f32_e32 v69, v69, v243
	v_add_f32_e32 v62, v62, v212
	v_add_f32_e32 v63, v63, v213
; __device__ __forceinline__ unsigned pack2(float a, float b) { unsigned r; asm("v_cvt_pk_bf16_f32 %0, %1, %2" : "=v"(r) : "v"(a), "v"(b)); return r; }
; __device__ __forceinline__ float bf2f(bf16_t h) { return __uint_as_float(((unsigned)h) << 16); }
;   __device__ __forceinline__ void c4(int g, int rig, int col, f32x4 v) const {
;     const size_t o = ((size_t)g * 2048 + rig) * 1024 + col;
;     f32x4 bs;
;     if (BASE_F32) bs = __builtin_nontemporal_load((const f32x4*)((const float*)base + o));
;     else {
;       const uint2 u = *(const uint2*)((const bf16_t*)base + o);
;       bs[0] = bf2f((bf16_t)(u.x & 0xffff)); bs[1] = bf2f((bf16_t)(u.x >> 16)); bs[2] = bf2f((bf16_t)(u.y & 0xffff)); bs[3] = bf2f((bf16_t)(u.y >> 16));
;     }
;     const f32x4 gt = *(const f32x4*)(gate + (size_t)g * 6144 + col);
;     f32x4 bi = {0.f, 0.f, 0.f, 0.f};
;     if (bias) bi = *(const f32x4*)(bias + col);
;     f32x4 r;
; #pragma unroll
;     for (int j = 0; j < 4; ++j) r[j] = bs[j] + gt[j] * (v[j] + bi[j]);
;     uint2 w; w.x = pack2(r[0], r[1]); w.y = pack2(r[2], r[3]);
;     *(uint2*)(X16 + o) = w;
;   }
	v_add_f32_e32 v64, v64, v214
	v_add_f32_e32 v65, v65, v215
	v_add_f32_e32 v58, v58, v216
	v_add_f32_e32 v59, v59, v217
	v_add_f32_e32 v60, v60, v218
	v_add_f32_e32 v61, v61, v219
	v_add_f32_e32 v54, v54, v220
	v_add_f32_e32 v55, v55, v221
	v_add_f32_e32 v56, v56, v222
	v_add_f32_e32 v57, v57, v223
	v_add_f32_e32 v50, v50, v224
	v_add_f32_e32 v51, v51, v225
	v_add_f32_e32 v52, v52, v226
	v_add_f32_e32 v53, v53, v227
	v_add_f32_e32 v46, v46, v228
	v_add_f32_e32 v47, v47, v229
	v_add_f32_e32 v48, v48, v230
	v_add_f32_e32 v49, v49, v231
	v_add_f32_e32 v42, v42, v232
	v_add_f32_e32 v43, v43, v233
	v_add_f32_e32 v44, v44, v234
	v_add_f32_e32 v45, v45, v235
	v_add_f32_e32 v38, v38, v236
	v_add_f32_e32 v39, v39, v237
	v_add_f32_e32 v40, v40, v238
	v_add_f32_e32 v41, v41, v239
	v_add_f32_e32 v34, v34, v240
	v_add_f32_e32 v35, v35, v241
	v_add_f32_e32 v36, v36, v242
	v_add_f32_e32 v37, v37, v243
	v_add_f32_e32 v30, v30, v212
	v_add_f32_e32 v31, v31, v213
	v_add_f32_e32 v32, v32, v214
	v_add_f32_e32 v33, v33, v215
	v_add_f32_e32 v26, v26, v216
	v_add_f32_e32 v27, v27, v217
	v_add_f32_e32 v28, v28, v218
	v_add_f32_e32 v29, v29, v219
	v_add_f32_e32 v22, v22, v220
	v_add_f32_e32 v23, v23, v221
	v_add_f32_e32 v24, v24, v222
	v_add_f32_e32 v25, v25, v223
	v_add_f32_e32 v18, v18, v224
	v_add_f32_e32 v19, v19, v225
	v_add_f32_e32 v20, v20, v226
	v_add_f32_e32 v21, v21, v227
	v_add_f32_e32 v14, v14, v228
	v_add_f32_e32 v15, v15, v229
	v_add_f32_e32 v16, v16, v230
	v_add_f32_e32 v17, v17, v231
	v_add_f32_e32 v10, v10, v232
	v_add_f32_e32 v11, v11, v233
	v_add_f32_e32 v12, v12, v234
	v_add_f32_e32 v13, v13, v235
	v_add_f32_e32 v6, v6, v236
	v_add_f32_e32 v7, v7, v237
	v_add_f32_e32 v8, v8, v238
	v_add_f32_e32 v9, v9, v239
	v_add_f32_e32 v2, v2, v240
	v_add_f32_e32 v3, v3, v241
	v_add_f32_e32 v4, v4, v242
	v_add_f32_e32 v5, v5, v243
	v_lshl_add_u64 v[214:215], v[140:141], 1, v[148:149]
	global_load_dwordx2 v[130:131], v[214:215], off
	global_load_dwordx2 v[132:133], v[214:215], off offset:32
	global_load_dwordx2 v[134:135], v[214:215], off offset:64
	global_load_dwordx2 v[136:137], v[214:215], off offset:96
	global_load_dwordx2 v[150:151], v[214:215], off offset:128
	global_load_dwordx2 v[152:153], v[214:215], off offset:160
	global_load_dwordx2 v[244:245], v[214:215], off offset:192
	global_load_dwordx2 v[246:247], v[214:215], off offset:224
	v_lshl_add_u64 v[216:217], v[214:215], 0, v[248:249]
	s_waitcnt vmcnt(6)
	v_lshlrev_b32_e32 v220, 16, v130
	v_and_b32_e32 v221, 0xffff0000, v130
	v_lshlrev_b32_e32 v222, 16, v131
	v_and_b32_e32 v223, 0xffff0000, v131
	v_fmac_f32_e32 v220, v180, v126
	v_fmac_f32_e32 v221, v181, v127
	v_fmac_f32_e32 v222, v182, v128
	v_fmac_f32_e32 v223, v183, v129
	v_cvt_pk_bf16_f32 v126, v220, v221
	v_cvt_pk_bf16_f32 v127, v222, v223
	v_lshlrev_b32_e32 v224, 16, v132
	v_and_b32_e32 v225, 0xffff0000, v132
	v_lshlrev_b32_e32 v226, 16, v133
	v_and_b32_e32 v227, 0xffff0000, v133
	v_fmac_f32_e32 v224, v184, v122
	v_fmac_f32_e32 v225, v185, v123
	v_fmac_f32_e32 v226, v186, v124
	v_fmac_f32_e32 v227, v187, v125
	v_cvt_pk_bf16_f32 v128, v224, v225
	v_cvt_pk_bf16_f32 v129, v226, v227
	s_nop 1
	v_permlane16_swap_b32 v126, v128
	v_permlane16_swap_b32 v127, v129
	global_store_dwordx4 v[216:217], v[126:129], off
	s_waitcnt vmcnt(5)
	v_lshlrev_b32_e32 v220, 16, v134
	v_and_b32_e32 v221, 0xffff0000, v134
	v_lshlrev_b32_e32 v222, 16, v135
	v_and_b32_e32 v223, 0xffff0000, v135
	v_fmac_f32_e32 v220, v188, v118
	v_fmac_f32_e32 v221, v189, v119
	v_fmac_f32_e32 v222, v190, v120
	v_fmac_f32_e32 v223, v191, v121
	v_cvt_pk_bf16_f32 v118, v220, v221
	v_cvt_pk_bf16_f32 v119, v222, v223
	v_lshlrev_b32_e32 v224, 16, v136
	v_and_b32_e32 v225, 0xffff0000, v136
	v_lshlrev_b32_e32 v226, 16, v137
	v_and_b32_e32 v227, 0xffff0000, v137
	v_fmac_f32_e32 v224, v192, v114
	v_fmac_f32_e32 v225, v193, v115
	v_fmac_f32_e32 v226, v194, v116
	v_fmac_f32_e32 v227, v195, v117
	v_cvt_pk_bf16_f32 v120, v224, v225
	v_cvt_pk_bf16_f32 v121, v226, v227
	s_nop 1
	v_permlane16_swap_b32 v118, v120
	v_permlane16_swap_b32 v119, v121
	global_store_dwordx4 v[216:217], v[118:121], off offset:64
	s_waitcnt vmcnt(4)
	v_lshlrev_b32_e32 v220, 16, v150
	v_and_b32_e32 v221, 0xffff0000, v150
	v_lshlrev_b32_e32 v222, 16, v151
	v_and_b32_e32 v223, 0xffff0000, v151
	v_fmac_f32_e32 v220, v196, v110
	v_fmac_f32_e32 v221, v197, v111
	v_fmac_f32_e32 v222, v198, v112
	v_fmac_f32_e32 v223, v199, v113
	v_cvt_pk_bf16_f32 v110, v220, v221
	v_cvt_pk_bf16_f32 v111, v222, v223
	v_lshlrev_b32_e32 v224, 16, v152
	v_and_b32_e32 v225, 0xffff0000, v152
	v_lshlrev_b32_e32 v226, 16, v153
	v_and_b32_e32 v227, 0xffff0000, v153
	v_fmac_f32_e32 v224, v200, v106
	v_fmac_f32_e32 v225, v201, v107
	v_fmac_f32_e32 v226, v202, v108
	v_fmac_f32_e32 v227, v203, v109
	v_cvt_pk_bf16_f32 v112, v224, v225
	v_cvt_pk_bf16_f32 v113, v226, v227
	s_nop 1
	v_permlane16_swap_b32 v110, v112
	v_permlane16_swap_b32 v111, v113
	global_store_dwordx4 v[216:217], v[110:113], off offset:128
	s_waitcnt vmcnt(3)
; __device__ __forceinline__ unsigned pack2(float a, float b) { unsigned r; asm("v_cvt_pk_bf16_f32 %0, %1, %2" : "=v"(r) : "v"(a), "v"(b)); return r; }
; __device__ __forceinline__ float bf2f(bf16_t h) { return __uint_as_float(((unsigned)h) << 16); }
;   __device__ __forceinline__ void c4(int g, int rig, int col, f32x4 v) const {
;     const size_t o = ((size_t)g * 2048 + rig) * 1024 + col;
;     f32x4 bs;
;     if (BASE_F32) bs = __builtin_nontemporal_load((const f32x4*)((const float*)base + o));
;     else {
;       const uint2 u = *(const uint2*)((const bf16_t*)base + o);
;       bs[0] = bf2f((bf16_t)(u.x & 0xffff)); bs[1] = bf2f((bf16_t)(u.x >> 16)); bs[2] = bf2f((bf16_t)(u.y & 0xffff)); bs[3] = bf2f((bf16_t)(u.y >> 16));
;     }
;     const f32x4 gt = *(const f32x4*)(gate + (size_t)g * 6144 + col);
;     f32x4 bi = {0.f, 0.f, 0.f, 0.f};
;     if (bias) bi = *(const f32x4*)(bias + col);
;     f32x4 r;
; #pragma unroll
;     for (int j = 0; j < 4; ++j) r[j] = bs[j] + gt[j] * (v[j] + bi[j]);
;     uint2 w; w.x = pack2(r[0], r[1]); w.y = pack2(r[2], r[3]);
;     *(uint2*)(X16 + o) = w;
;   }
	v_lshlrev_b32_e32 v220, 16, v244
	v_and_b32_e32 v221, 0xffff0000, v244
	v_lshlrev_b32_e32 v222, 16, v245
	v_and_b32_e32 v223, 0xffff0000, v245
	v_fmac_f32_e32 v220, v204, v102
	v_fmac_f32_e32 v221, v205, v103
	v_fmac_f32_e32 v222, v206, v104
	v_fmac_f32_e32 v223, v207, v105
	v_cvt_pk_bf16_f32 v102, v220, v221
	v_cvt_pk_bf16_f32 v103, v222, v223
	v_lshlrev_b32_e32 v224, 16, v246
	v_and_b32_e32 v225, 0xffff0000, v246
	v_lshlrev_b32_e32 v226, 16, v247
	v_and_b32_e32 v227, 0xffff0000, v247
	v_fmac_f32_e32 v224, v208, v98
	v_fmac_f32_e32 v225, v209, v99
	v_fmac_f32_e32 v226, v210, v100
	v_fmac_f32_e32 v227, v211, v101
	v_cvt_pk_bf16_f32 v104, v224, v225
	v_cvt_pk_bf16_f32 v105, v226, v227
	s_nop 1
	v_permlane16_swap_b32 v102, v104
	v_permlane16_swap_b32 v103, v105
	global_store_dwordx4 v[216:217], v[102:105], off offset:192
	s_nop 1
	v_or_b32_e32 v218, 16, v144
	v_lshlrev_b32_e32 v218, 10, v218
	v_mov_b32_e32 v219, 0
	v_lshl_add_u64 v[212:213], v[218:219], 0, v[146:147]
	v_lshl_add_u64 v[212:213], v[212:213], 1, s[24:25]
	v_lshl_add_u64 v[214:215], v[140:141], 1, v[212:213]
	global_load_dwordx2 v[130:131], v[214:215], off
	global_load_dwordx2 v[132:133], v[214:215], off offset:32
	global_load_dwordx2 v[134:135], v[214:215], off offset:64
	global_load_dwordx2 v[136:137], v[214:215], off offset:96
	global_load_dwordx2 v[150:151], v[214:215], off offset:128
	global_load_dwordx2 v[152:153], v[214:215], off offset:160
	global_load_dwordx2 v[244:245], v[214:215], off offset:192
	global_load_dwordx2 v[246:247], v[214:215], off offset:224
	v_lshl_add_u64 v[216:217], v[214:215], 0, v[248:249]
	s_waitcnt vmcnt(6)
	v_lshlrev_b32_e32 v220, 16, v130
	v_and_b32_e32 v221, 0xffff0000, v130
	v_lshlrev_b32_e32 v222, 16, v131
	v_and_b32_e32 v223, 0xffff0000, v131
	v_fmac_f32_e32 v220, v180, v94
	v_fmac_f32_e32 v221, v181, v95
	v_fmac_f32_e32 v222, v182, v96
	v_fmac_f32_e32 v223, v183, v97
	v_cvt_pk_bf16_f32 v94, v220, v221
	v_cvt_pk_bf16_f32 v95, v222, v223
	v_lshlrev_b32_e32 v224, 16, v132
	v_and_b32_e32 v225, 0xffff0000, v132
	v_lshlrev_b32_e32 v226, 16, v133
	v_and_b32_e32 v227, 0xffff0000, v133
	v_fmac_f32_e32 v224, v184, v90
	v_fmac_f32_e32 v225, v185, v91
	v_fmac_f32_e32 v226, v186, v92
	v_fmac_f32_e32 v227, v187, v93
	v_cvt_pk_bf16_f32 v96, v224, v225
	v_cvt_pk_bf16_f32 v97, v226, v227
	s_nop 1
	v_permlane16_swap_b32 v94, v96
	v_permlane16_swap_b32 v95, v97
	global_store_dwordx4 v[216:217], v[94:97], off
	s_waitcnt vmcnt(5)
	v_lshlrev_b32_e32 v220, 16, v134
	v_and_b32_e32 v221, 0xffff0000, v134
	v_lshlrev_b32_e32 v222, 16, v135
	v_and_b32_e32 v223, 0xffff0000, v135
	v_fmac_f32_e32 v220, v188, v86
	v_fmac_f32_e32 v221, v189, v87
	v_fmac_f32_e32 v222, v190, v88
	v_fmac_f32_e32 v223, v191, v89
	v_cvt_pk_bf16_f32 v86, v220, v221
	v_cvt_pk_bf16_f32 v87, v222, v223
	v_lshlrev_b32_e32 v224, 16, v136
	v_and_b32_e32 v225, 0xffff0000, v136
	v_lshlrev_b32_e32 v226, 16, v137
	v_and_b32_e32 v227, 0xffff0000, v137
	v_fmac_f32_e32 v224, v192, v82
	v_fmac_f32_e32 v225, v193, v83
	v_fmac_f32_e32 v226, v194, v84
	v_fmac_f32_e32 v227, v195, v85
	v_cvt_pk_bf16_f32 v88, v224, v225
	v_cvt_pk_bf16_f32 v89, v226, v227
	s_nop 1
	v_permlane16_swap_b32 v86, v88
	v_permlane16_swap_b32 v87, v89
	global_store_dwordx4 v[216:217], v[86:89], off offset:64
	s_waitcnt vmcnt(4)
	v_lshlrev_b32_e32 v220, 16, v150
	v_and_b32_e32 v221, 0xffff0000, v150
	v_lshlrev_b32_e32 v222, 16, v151
	v_and_b32_e32 v223, 0xffff0000, v151
	v_fmac_f32_e32 v220, v196, v78
	v_fmac_f32_e32 v221, v197, v79
	v_fmac_f32_e32 v222, v198, v80
	v_fmac_f32_e32 v223, v199, v81
	v_cvt_pk_bf16_f32 v78, v220, v221
	v_cvt_pk_bf16_f32 v79, v222, v223
	v_lshlrev_b32_e32 v224, 16, v152
	v_and_b32_e32 v225, 0xffff0000, v152
	v_lshlrev_b32_e32 v226, 16, v153
	v_and_b32_e32 v227, 0xffff0000, v153
	v_fmac_f32_e32 v224, v200, v74
	v_fmac_f32_e32 v225, v201, v75
	v_fmac_f32_e32 v226, v202, v76
	v_fmac_f32_e32 v227, v203, v77
	v_cvt_pk_bf16_f32 v80, v224, v225
	v_cvt_pk_bf16_f32 v81, v226, v227
	s_nop 1
	v_permlane16_swap_b32 v78, v80
	v_permlane16_swap_b32 v79, v81
	global_store_dwordx4 v[216:217], v[78:81], off offset:128
	s_waitcnt vmcnt(3)
	v_lshlrev_b32_e32 v220, 16, v244
	v_and_b32_e32 v221, 0xffff0000, v244
	v_lshlrev_b32_e32 v222, 16, v245
	v_and_b32_e32 v223, 0xffff0000, v245
	v_fmac_f32_e32 v220, v204, v70
	v_fmac_f32_e32 v221, v205, v71
	v_fmac_f32_e32 v222, v206, v72
	v_fmac_f32_e32 v223, v207, v73
	v_cvt_pk_bf16_f32 v70, v220, v221
	v_cvt_pk_bf16_f32 v71, v222, v223
	v_lshlrev_b32_e32 v224, 16, v246
	v_and_b32_e32 v225, 0xffff0000, v246
	v_lshlrev_b32_e32 v226, 16, v247
	v_and_b32_e32 v227, 0xffff0000, v247
	v_fmac_f32_e32 v224, v208, v66
	v_fmac_f32_e32 v225, v209, v67
	v_fmac_f32_e32 v226, v210, v68
	v_fmac_f32_e32 v227, v211, v69
	v_cvt_pk_bf16_f32 v72, v224, v225
	v_cvt_pk_bf16_f32 v73, v226, v227
	s_nop 1
	v_permlane16_swap_b32 v70, v72
	v_permlane16_swap_b32 v71, v73
	global_store_dwordx4 v[216:217], v[70:73], off offset:192
	s_nop 1
	v_or_b32_e32 v218, 32, v144
	v_lshlrev_b32_e32 v218, 10, v218
	v_mov_b32_e32 v219, 0
	v_lshl_add_u64 v[212:213], v[218:219], 0, v[146:147]
	v_lshl_add_u64 v[212:213], v[212:213], 1, s[24:25]
	v_lshl_add_u64 v[214:215], v[140:141], 1, v[212:213]
	global_load_dwordx2 v[130:131], v[214:215], off
	global_load_dwordx2 v[132:133], v[214:215], off offset:32
	global_load_dwordx2 v[134:135], v[214:215], off offset:64
	global_load_dwordx2 v[136:137], v[214:215], off offset:96
	global_load_dwordx2 v[150:151], v[214:215], off offset:128
	global_load_dwordx2 v[152:153], v[214:215], off offset:160
	global_load_dwordx2 v[244:245], v[214:215], off offset:192
	global_load_dwordx2 v[246:247], v[214:215], off offset:224
	v_lshl_add_u64 v[216:217], v[214:215], 0, v[248:249]
	s_waitcnt vmcnt(6)
; __device__ __forceinline__ unsigned pack2(float a, float b) { unsigned r; asm("v_cvt_pk_bf16_f32 %0, %1, %2" : "=v"(r) : "v"(a), "v"(b)); return r; }
; __device__ __forceinline__ float bf2f(bf16_t h) { return __uint_as_float(((unsigned)h) << 16); }
;   __device__ __forceinline__ void c4(int g, int rig, int col, f32x4 v) const {
;     const size_t o = ((size_t)g * 2048 + rig) * 1024 + col;
;     f32x4 bs;
;     if (BASE_F32) bs = __builtin_nontemporal_load((const f32x4*)((const float*)base + o));
;     else {
;       const uint2 u = *(const uint2*)((const bf16_t*)base + o);
;       bs[0] = bf2f((bf16_t)(u.x & 0xffff)); bs[1] = bf2f((bf16_t)(u.x >> 16)); bs[2] = bf2f((bf16_t)(u.y & 0xffff)); bs[3] = bf2f((bf16_t)(u.y >> 16));
;     }
;     const f32x4 gt = *(const f32x4*)(gate + (size_t)g * 6144 + col);
;     f32x4 bi = {0.f, 0.f, 0.f, 0.f};
;     if (bias) bi = *(const f32x4*)(bias + col);
;     f32x4 r;
; #pragma unroll
;     for (int j = 0; j < 4; ++j) r[j] = bs[j] + gt[j] * (v[j] + bi[j]);
;     uint2 w; w.x = pack2(r[0], r[1]); w.y = pack2(r[2], r[3]);
;     *(uint2*)(X16 + o) = w;
;   }
	v_lshlrev_b32_e32 v220, 16, v130
	v_and_b32_e32 v221, 0xffff0000, v130
	v_lshlrev_b32_e32 v222, 16, v131
	v_and_b32_e32 v223, 0xffff0000, v131
	v_fmac_f32_e32 v220, v180, v62
	v_fmac_f32_e32 v221, v181, v63
	v_fmac_f32_e32 v222, v182, v64
	v_fmac_f32_e32 v223, v183, v65
	v_cvt_pk_bf16_f32 v62, v220, v221
	v_cvt_pk_bf16_f32 v63, v222, v223
	v_lshlrev_b32_e32 v224, 16, v132
	v_and_b32_e32 v225, 0xffff0000, v132
	v_lshlrev_b32_e32 v226, 16, v133
	v_and_b32_e32 v227, 0xffff0000, v133
	v_fmac_f32_e32 v224, v184, v58
	v_fmac_f32_e32 v225, v185, v59
	v_fmac_f32_e32 v226, v186, v60
	v_fmac_f32_e32 v227, v187, v61
	v_cvt_pk_bf16_f32 v64, v224, v225
	v_cvt_pk_bf16_f32 v65, v226, v227
	s_nop 1
	v_permlane16_swap_b32 v62, v64
	v_permlane16_swap_b32 v63, v65
	global_store_dwordx4 v[216:217], v[62:65], off
	s_waitcnt vmcnt(5)
	v_lshlrev_b32_e32 v220, 16, v134
	v_and_b32_e32 v221, 0xffff0000, v134
	v_lshlrev_b32_e32 v222, 16, v135
	v_and_b32_e32 v223, 0xffff0000, v135
	v_fmac_f32_e32 v220, v188, v54
	v_fmac_f32_e32 v221, v189, v55
	v_fmac_f32_e32 v222, v190, v56
	v_fmac_f32_e32 v223, v191, v57
	v_cvt_pk_bf16_f32 v54, v220, v221
	v_cvt_pk_bf16_f32 v55, v222, v223
	v_lshlrev_b32_e32 v224, 16, v136
	v_and_b32_e32 v225, 0xffff0000, v136
	v_lshlrev_b32_e32 v226, 16, v137
	v_and_b32_e32 v227, 0xffff0000, v137
	v_fmac_f32_e32 v224, v192, v50
	v_fmac_f32_e32 v225, v193, v51
	v_fmac_f32_e32 v226, v194, v52
	v_fmac_f32_e32 v227, v195, v53
	v_cvt_pk_bf16_f32 v56, v224, v225
	v_cvt_pk_bf16_f32 v57, v226, v227
	s_nop 1
	v_permlane16_swap_b32 v54, v56
	v_permlane16_swap_b32 v55, v57
	global_store_dwordx4 v[216:217], v[54:57], off offset:64
	s_waitcnt vmcnt(4)
	v_lshlrev_b32_e32 v220, 16, v150
	v_and_b32_e32 v221, 0xffff0000, v150
	v_lshlrev_b32_e32 v222, 16, v151
	v_and_b32_e32 v223, 0xffff0000, v151
	v_fmac_f32_e32 v220, v196, v46
	v_fmac_f32_e32 v221, v197, v47
	v_fmac_f32_e32 v222, v198, v48
	v_fmac_f32_e32 v223, v199, v49
	v_cvt_pk_bf16_f32 v46, v220, v221
	v_cvt_pk_bf16_f32 v47, v222, v223
	v_lshlrev_b32_e32 v224, 16, v152
	v_and_b32_e32 v225, 0xffff0000, v152
	v_lshlrev_b32_e32 v226, 16, v153
	v_and_b32_e32 v227, 0xffff0000, v153
	v_fmac_f32_e32 v224, v200, v42
	v_fmac_f32_e32 v225, v201, v43
	v_fmac_f32_e32 v226, v202, v44
	v_fmac_f32_e32 v227, v203, v45
	v_cvt_pk_bf16_f32 v48, v224, v225
	v_cvt_pk_bf16_f32 v49, v226, v227
	s_nop 1
	v_permlane16_swap_b32 v46, v48
	v_permlane16_swap_b32 v47, v49
	global_store_dwordx4 v[216:217], v[46:49], off offset:128
	s_waitcnt vmcnt(3)
	v_lshlrev_b32_e32 v220, 16, v244
	v_and_b32_e32 v221, 0xffff0000, v244
	v_lshlrev_b32_e32 v222, 16, v245
	v_and_b32_e32 v223, 0xffff0000, v245
	v_fmac_f32_e32 v220, v204, v38
	v_fmac_f32_e32 v221, v205, v39
	v_fmac_f32_e32 v222, v206, v40
	v_fmac_f32_e32 v223, v207, v41
	v_cvt_pk_bf16_f32 v38, v220, v221
	v_cvt_pk_bf16_f32 v39, v222, v223
	v_lshlrev_b32_e32 v224, 16, v246
	v_and_b32_e32 v225, 0xffff0000, v246
	v_lshlrev_b32_e32 v226, 16, v247
	v_and_b32_e32 v227, 0xffff0000, v247
	v_fmac_f32_e32 v224, v208, v34
	v_fmac_f32_e32 v225, v209, v35
	v_fmac_f32_e32 v226, v210, v36
	v_fmac_f32_e32 v227, v211, v37
	v_cvt_pk_bf16_f32 v40, v224, v225
	v_cvt_pk_bf16_f32 v41, v226, v227
	s_nop 1
	v_permlane16_swap_b32 v38, v40
	v_permlane16_swap_b32 v39, v41
	global_store_dwordx4 v[216:217], v[38:41], off offset:192
	s_nop 1
	v_or_b32_e32 v218, 48, v144
	v_lshlrev_b32_e32 v218, 10, v218
	v_mov_b32_e32 v219, 0
	v_lshl_add_u64 v[212:213], v[218:219], 0, v[146:147]
	v_lshl_add_u64 v[212:213], v[212:213], 1, s[24:25]
	v_lshl_add_u64 v[214:215], v[140:141], 1, v[212:213]
	global_load_dwordx2 v[130:131], v[214:215], off
	global_load_dwordx2 v[132:133], v[214:215], off offset:32
	global_load_dwordx2 v[134:135], v[214:215], off offset:64
	global_load_dwordx2 v[136:137], v[214:215], off offset:96
	global_load_dwordx2 v[150:151], v[214:215], off offset:128
	global_load_dwordx2 v[152:153], v[214:215], off offset:160
	global_load_dwordx2 v[244:245], v[214:215], off offset:192
	global_load_dwordx2 v[246:247], v[214:215], off offset:224
	v_lshl_add_u64 v[216:217], v[214:215], 0, v[248:249]
	s_waitcnt vmcnt(6)
; __device__ __forceinline__ unsigned pack2(float a, float b) { unsigned r; asm("v_cvt_pk_bf16_f32 %0, %1, %2" : "=v"(r) : "v"(a), "v"(b)); return r; }
; __device__ __forceinline__ float bf2f(bf16_t h) { return __uint_as_float(((unsigned)h) << 16); }
;   __device__ __forceinline__ void c4(int g, int rig, int col, f32x4 v) const {
;     const size_t o = ((size_t)g * 2048 + rig) * 1024 + col;
;     f32x4 bs;
;     if (BASE_F32) bs = __builtin_nontemporal_load((const f32x4*)((const float*)base + o));
;     else {
;       const uint2 u = *(const uint2*)((const bf16_t*)base + o);
;       bs[0] = bf2f((bf16_t)(u.x & 0xffff)); bs[1] = bf2f((bf16_t)(u.x >> 16)); bs[2] = bf2f((bf16_t)(u.y & 0xffff)); bs[3] = bf2f((bf16_t)(u.y >> 16));
;     }
;     const f32x4 gt = *(const f32x4*)(gate + (size_t)g * 6144 + col);
;     f32x4 bi = {0.f, 0.f, 0.f, 0.f};
;     if (bias) bi = *(const f32x4*)(bias + col);
;     f32x4 r;
; #pragma unroll
;     for (int j = 0; j < 4; ++j) r[j] = bs[j] + gt[j] * (v[j] + bi[j]);
;     uint2 w; w.x = pack2(r[0], r[1]); w.y = pack2(r[2], r[3]);
;     *(uint2*)(X16 + o) = w;
;   }
	v_lshlrev_b32_e32 v220, 16, v130
	v_and_b32_e32 v221, 0xffff0000, v130
	v_lshlrev_b32_e32 v222, 16, v131
	v_and_b32_e32 v223, 0xffff0000, v131
	v_fmac_f32_e32 v220, v180, v30
	v_fmac_f32_e32 v221, v181, v31
	v_fmac_f32_e32 v222, v182, v32
	v_fmac_f32_e32 v223, v183, v33
	v_cvt_pk_bf16_f32 v30, v220, v221
	v_cvt_pk_bf16_f32 v31, v222, v223
	v_lshlrev_b32_e32 v224, 16, v132
	v_and_b32_e32 v225, 0xffff0000, v132
	v_lshlrev_b32_e32 v226, 16, v133
	v_and_b32_e32 v227, 0xffff0000, v133
	v_fmac_f32_e32 v224, v184, v26
	v_fmac_f32_e32 v225, v185, v27
	v_fmac_f32_e32 v226, v186, v28
	v_fmac_f32_e32 v227, v187, v29
	v_cvt_pk_bf16_f32 v32, v224, v225
	v_cvt_pk_bf16_f32 v33, v226, v227
	s_nop 1
	v_permlane16_swap_b32 v30, v32
	v_permlane16_swap_b32 v31, v33
	global_store_dwordx4 v[216:217], v[30:33], off
	s_waitcnt vmcnt(5)
	v_lshlrev_b32_e32 v220, 16, v134
	v_and_b32_e32 v221, 0xffff0000, v134
	v_lshlrev_b32_e32 v222, 16, v135
	v_and_b32_e32 v223, 0xffff0000, v135
	v_fmac_f32_e32 v220, v188, v22
	v_fmac_f32_e32 v221, v189, v23
	v_fmac_f32_e32 v222, v190, v24
	v_fmac_f32_e32 v223, v191, v25
	v_cvt_pk_bf16_f32 v22, v220, v221
	v_cvt_pk_bf16_f32 v23, v222, v223
	v_lshlrev_b32_e32 v224, 16, v136
	v_and_b32_e32 v225, 0xffff0000, v136
	v_lshlrev_b32_e32 v226, 16, v137
	v_and_b32_e32 v227, 0xffff0000, v137
	v_fmac_f32_e32 v224, v192, v18
	v_fmac_f32_e32 v225, v193, v19
	v_fmac_f32_e32 v226, v194, v20
	v_fmac_f32_e32 v227, v195, v21
	v_cvt_pk_bf16_f32 v24, v224, v225
	v_cvt_pk_bf16_f32 v25, v226, v227
	s_nop 1
	v_permlane16_swap_b32 v22, v24
	v_permlane16_swap_b32 v23, v25
	global_store_dwordx4 v[216:217], v[22:25], off offset:64
	s_waitcnt vmcnt(4)
	v_lshlrev_b32_e32 v220, 16, v150
	v_and_b32_e32 v221, 0xffff0000, v150
	v_lshlrev_b32_e32 v222, 16, v151
	v_and_b32_e32 v223, 0xffff0000, v151
	v_fmac_f32_e32 v220, v196, v14
	v_fmac_f32_e32 v221, v197, v15
	v_fmac_f32_e32 v222, v198, v16
	v_fmac_f32_e32 v223, v199, v17
	v_cvt_pk_bf16_f32 v14, v220, v221
	v_cvt_pk_bf16_f32 v15, v222, v223
	v_lshlrev_b32_e32 v224, 16, v152
	v_and_b32_e32 v225, 0xffff0000, v152
	v_lshlrev_b32_e32 v226, 16, v153
	v_and_b32_e32 v227, 0xffff0000, v153
	v_fmac_f32_e32 v224, v200, v10
	v_fmac_f32_e32 v225, v201, v11
	v_fmac_f32_e32 v226, v202, v12
	v_fmac_f32_e32 v227, v203, v13
	v_cvt_pk_bf16_f32 v16, v224, v225
	v_cvt_pk_bf16_f32 v17, v226, v227
	s_nop 1
	v_permlane16_swap_b32 v14, v16
	v_permlane16_swap_b32 v15, v17
	global_store_dwordx4 v[216:217], v[14:17], off offset:128
	s_waitcnt vmcnt(3)
	v_lshlrev_b32_e32 v220, 16, v244
	v_and_b32_e32 v221, 0xffff0000, v244
	v_lshlrev_b32_e32 v222, 16, v245
	v_and_b32_e32 v223, 0xffff0000, v245
	v_fmac_f32_e32 v220, v204, v6
	v_fmac_f32_e32 v221, v205, v7
	v_fmac_f32_e32 v222, v206, v8
	v_fmac_f32_e32 v223, v207, v9
	v_cvt_pk_bf16_f32 v6, v220, v221
	v_cvt_pk_bf16_f32 v7, v222, v223
	v_lshlrev_b32_e32 v224, 16, v246
	v_and_b32_e32 v225, 0xffff0000, v246
	v_lshlrev_b32_e32 v226, 16, v247
	v_and_b32_e32 v227, 0xffff0000, v247
	v_fmac_f32_e32 v224, v208, v2
	v_fmac_f32_e32 v225, v209, v3
	v_fmac_f32_e32 v226, v210, v4
	v_fmac_f32_e32 v227, v211, v5
	v_cvt_pk_bf16_f32 v8, v224, v225
	v_cvt_pk_bf16_f32 v9, v226, v227
	s_nop 1
	v_permlane16_swap_b32 v6, v8
	v_permlane16_swap_b32 v7, v9
	global_store_dwordx4 v[216:217], v[6:9], off offset:192
	s_nop 1
	s_mov_b64 s[6:7], exec
	s_branch .LBB0_3110
